# also drop the vmcnt(0) drain inside the accumulator zeroing block between GEMM units
# baseline (speedup 1.0000x reference)
; template <class Epi, class Sched, bool ALIGN_EPI = false, bool SP2 = false>
; __device__ __forceinline__ void gemm_phase(PG8_LAS unsigned char* lds, const Gemm g, const Sched& S, const Epi& E) {
;     ...
;         if (epi_now) {
; #pragma unroll
;         for (int a = 0; a < 2; ++a)
; #pragma unroll
;             for (int b = 0; b < 2; ++b)
; #pragma unroll
;                 for (int m = 0; m < 4; ++m)
; #pragma unroll
;                     for (int n = 0; n < 2; ++n) acc[a][b][m][n] = (f32x4){0.f, 0.f, 0.f, 0.f};
;         }
;         cur = nxt; cA = nA; cB = nB; ++ui;
.LBB0_62:
	s_add_u32 s44, s66, 0x80
	s_addc_u32 s45, s67, 0
	s_add_u32 s19, s46, 0x100
	v_mov_b32_e32 v0, 0
	s_addc_u32 s20, s47, 0
	s_mov_b32 s46, 0
	v_mov_b32_e32 v1, v0
	v_mov_b32_e32 v2, v0
	v_mov_b32_e32 v3, v0
	v_mov_b32_e32 v4, v0
	v_mov_b32_e32 v5, v0
	v_mov_b32_e32 v6, v0
	v_mov_b32_e32 v7, v0
	v_mov_b32_e32 v16, v0
	v_mov_b32_e32 v17, v0
	v_mov_b32_e32 v18, v0
	v_mov_b32_e32 v19, v0
	v_mov_b32_e32 v20, v0
	v_mov_b32_e32 v21, v0
	v_mov_b32_e32 v22, v0
	v_mov_b32_e32 v23, v0
	v_mov_b32_e32 v32, v0
	v_mov_b32_e32 v33, v0
	v_mov_b32_e32 v34, v0
	v_mov_b32_e32 v35, v0
	v_mov_b32_e32 v36, v0
	v_mov_b32_e32 v37, v0
	v_mov_b32_e32 v38, v0
	v_mov_b32_e32 v39, v0
	v_mov_b32_e32 v48, v0
	v_mov_b32_e32 v49, v0
	v_mov_b32_e32 v50, v0
	v_mov_b32_e32 v51, v0
	v_mov_b32_e32 v52, v0
	v_mov_b32_e32 v53, v0
	v_mov_b32_e32 v54, v0
	v_mov_b32_e32 v55, v0
	v_mov_b32_e32 v8, v0
	v_mov_b32_e32 v9, v0
	v_mov_b32_e32 v10, v0
	v_mov_b32_e32 v11, v0
	v_mov_b32_e32 v12, v0
	v_mov_b32_e32 v13, v0
	v_mov_b32_e32 v14, v0
	v_mov_b32_e32 v15, v0
	v_mov_b32_e32 v24, v0
	v_mov_b32_e32 v25, v0
	v_mov_b32_e32 v26, v0
	v_mov_b32_e32 v27, v0
	v_mov_b32_e32 v28, v0
	v_mov_b32_e32 v29, v0
	v_mov_b32_e32 v30, v0
	v_mov_b32_e32 v31, v0
	v_mov_b32_e32 v40, v0
	v_mov_b32_e32 v41, v0
	v_mov_b32_e32 v42, v0
	v_mov_b32_e32 v43, v0
	v_mov_b32_e32 v44, v0
	v_mov_b32_e32 v45, v0
	v_mov_b32_e32 v46, v0
	v_mov_b32_e32 v47, v0
	v_mov_b32_e32 v56, v0
	v_mov_b32_e32 v57, v0
	v_mov_b32_e32 v58, v0
	v_mov_b32_e32 v59, v0
	v_mov_b32_e32 v60, v0
	v_mov_b32_e32 v61, v0
	v_mov_b32_e32 v62, v0
	v_mov_b32_e32 v63, v0
	v_mov_b32_e32 v64, v0
	v_mov_b32_e32 v65, v0
	v_mov_b32_e32 v66, v0
	v_mov_b32_e32 v67, v0
	v_mov_b32_e32 v68, v0
	v_mov_b32_e32 v69, v0
	v_mov_b32_e32 v70, v0
	v_mov_b32_e32 v71, v0
	v_mov_b32_e32 v80, v0
	v_mov_b32_e32 v81, v0
	v_mov_b32_e32 v82, v0
	v_mov_b32_e32 v83, v0
	v_mov_b32_e32 v84, v0
	v_mov_b32_e32 v85, v0
	v_mov_b32_e32 v86, v0
	v_mov_b32_e32 v87, v0
	v_mov_b32_e32 v96, v0
	v_mov_b32_e32 v97, v0
	v_mov_b32_e32 v98, v0
	v_mov_b32_e32 v99, v0
	v_mov_b32_e32 v100, v0
	v_mov_b32_e32 v101, v0
	v_mov_b32_e32 v102, v0
	v_mov_b32_e32 v103, v0
	v_mov_b32_e32 v112, v0
	v_mov_b32_e32 v113, v0
	v_mov_b32_e32 v114, v0
	v_mov_b32_e32 v115, v0
	v_mov_b32_e32 v116, v0
	v_mov_b32_e32 v117, v0
	v_mov_b32_e32 v118, v0
	v_mov_b32_e32 v119, v0
	v_mov_b32_e32 v72, v0
	v_mov_b32_e32 v73, v0
	v_mov_b32_e32 v74, v0
	v_mov_b32_e32 v75, v0
	v_mov_b32_e32 v76, v0
	v_mov_b32_e32 v77, v0
	v_mov_b32_e32 v78, v0
	v_mov_b32_e32 v79, v0
	v_mov_b32_e32 v88, v0
	v_mov_b32_e32 v89, v0
	v_mov_b32_e32 v90, v0
	v_mov_b32_e32 v91, v0
	v_mov_b32_e32 v92, v0
	v_mov_b32_e32 v93, v0
	v_mov_b32_e32 v94, v0
	v_mov_b32_e32 v95, v0
	v_mov_b32_e32 v104, v0
	v_mov_b32_e32 v105, v0
	v_mov_b32_e32 v106, v0
	v_mov_b32_e32 v107, v0
	v_mov_b32_e32 v108, v0
	v_mov_b32_e32 v109, v0
	v_mov_b32_e32 v110, v0
	v_mov_b32_e32 v111, v0
	v_mov_b32_e32 v120, v0
	v_mov_b32_e32 v121, v0
	v_mov_b32_e32 v122, v0
	v_mov_b32_e32 v123, v0
	v_mov_b32_e32 v124, v0
	v_mov_b32_e32 v125, v0
	v_mov_b32_e32 v126, v0
	v_mov_b32_e32 v127, v0

;     __device__ __forceinline__ const char* aptr(const Unit& u, const Gemm& g) const { return (const char*)g.A + (long)(u.pm >> 4) * g.adj; }
;     __device__ __forceinline__ const char* bptr(const Unit&, const Gemm& g) const { return (const char*)g.Bt; }
;     __device__ __forceinline__ bool next(int i, Unit& u) const { const int r = i / 9, tile = t0 + r * ts; if (r >= nr || tile >= 512) return false; u.pm = tile >> 2; u.pn = tile & 3; u.kind = i % 9; return true; }
; template <class Epi, class Sched, bool ALIGN_EPI = false, bool SP2 = false>
; __device__ __forceinline__ void gemm_phase(PG8_LAS unsigned char* lds, const Gemm g, const Sched& S, const Epi& E) {
;     ...
;         const bool has_next = S.next(ui + 1, nxt);
;         const char* nA = has_next ? S.aptr(nxt, g) + (size_t)nxt.pm * tstep : cA; const char* nB = has_next ? S.bptr(nxt, g) + (size_t)nxt.pn * tstep : cB;
;     ...
;         if (epi_now) {
; #pragma unroll
;         for (int a = 0; a < 2; ++a)
; #pragma unroll
;             for (int b = 0; b < 2; ++b)
; #pragma unroll
;                 for (int m = 0; m < 4; ++m)
; #pragma unroll
;                     for (int n = 0; n < 2; ++n) acc[a][b][m][n] = (f32x4){0.f, 0.f, 0.f, 0.f};
;         }
;         cur = nxt; cA = nA; cB = nB; ++ui;
.LBB0_199:
	s_ashr_i32 s51, s50, 31
	s_lshl_b64 s[18:19], s[50:51], 19
	s_add_u32 s52, s23, s18
	s_addc_u32 s53, s62, s19
	s_and_b64 s[18:19], s[40:41], exec
	s_cselect_b32 s18, s53, s57
	s_cselect_b32 s19, s52, s56
	s_ashr_i32 s49, s48, 31
	s_lshl_b64 s[54:55], s[48:49], 19
	s_add_u32 s54, s14, s54
	s_addc_u32 s55, s22, s55
	s_and_b64 s[60:61], s[40:41], exec
	s_cselect_b32 s20, s55, s59
	s_cselect_b32 s43, s54, s58
	s_add_u32 s56, s56, 0x40080
	s_addc_u32 s57, s57, 0
	s_add_u32 s49, s58, 0x100
	v_mov_b32_e32 v0, 0
	s_addc_u32 s51, s59, 0
	s_mov_b32 s76, -2
	v_mov_b32_e32 v1, v0
	v_mov_b32_e32 v2, v0
	v_mov_b32_e32 v3, v0
	v_mov_b32_e32 v4, v0
	v_mov_b32_e32 v5, v0
	v_mov_b32_e32 v6, v0
	v_mov_b32_e32 v7, v0
	v_mov_b32_e32 v12, v0
	v_mov_b32_e32 v13, v0
	v_mov_b32_e32 v14, v0
	v_mov_b32_e32 v15, v0
	v_mov_b32_e32 v20, v0
	v_mov_b32_e32 v21, v0
	v_mov_b32_e32 v22, v0
	v_mov_b32_e32 v23, v0
	v_mov_b32_e32 v28, v0
	v_mov_b32_e32 v29, v0
	v_mov_b32_e32 v30, v0
	v_mov_b32_e32 v31, v0
	v_mov_b32_e32 v36, v0
	v_mov_b32_e32 v37, v0
	v_mov_b32_e32 v38, v0
	v_mov_b32_e32 v39, v0
	v_mov_b32_e32 v44, v0
	v_mov_b32_e32 v45, v0
	v_mov_b32_e32 v46, v0
	v_mov_b32_e32 v47, v0
	v_mov_b32_e32 v52, v0
	v_mov_b32_e32 v53, v0
	v_mov_b32_e32 v54, v0
	v_mov_b32_e32 v55, v0
	v_mov_b32_e32 v8, v0
	v_mov_b32_e32 v9, v0
	v_mov_b32_e32 v10, v0
	v_mov_b32_e32 v11, v0
	v_mov_b32_e32 v16, v0
	v_mov_b32_e32 v17, v0
	v_mov_b32_e32 v18, v0
	v_mov_b32_e32 v19, v0
	v_mov_b32_e32 v24, v0
	v_mov_b32_e32 v25, v0
	v_mov_b32_e32 v26, v0
	v_mov_b32_e32 v27, v0
	v_mov_b32_e32 v32, v0
	v_mov_b32_e32 v33, v0
	v_mov_b32_e32 v34, v0
	v_mov_b32_e32 v35, v0
	v_mov_b32_e32 v40, v0
	v_mov_b32_e32 v41, v0
	v_mov_b32_e32 v42, v0
	v_mov_b32_e32 v43, v0
	v_mov_b32_e32 v48, v0
	v_mov_b32_e32 v49, v0
	v_mov_b32_e32 v50, v0
	v_mov_b32_e32 v51, v0
	v_mov_b32_e32 v56, v0
	v_mov_b32_e32 v57, v0
	v_mov_b32_e32 v58, v0
	v_mov_b32_e32 v59, v0
	v_mov_b32_e32 v60, v0
	v_mov_b32_e32 v61, v0
	v_mov_b32_e32 v62, v0
	v_mov_b32_e32 v63, v0
	v_mov_b32_e32 v64, v0
	v_mov_b32_e32 v65, v0
	v_mov_b32_e32 v66, v0
	v_mov_b32_e32 v67, v0
	v_mov_b32_e32 v68, v0
	v_mov_b32_e32 v69, v0
	v_mov_b32_e32 v70, v0
	v_mov_b32_e32 v71, v0
	v_mov_b32_e32 v76, v0
	v_mov_b32_e32 v77, v0
	v_mov_b32_e32 v78, v0
	v_mov_b32_e32 v79, v0
	v_mov_b32_e32 v84, v0
	v_mov_b32_e32 v85, v0
	v_mov_b32_e32 v86, v0
	v_mov_b32_e32 v87, v0
	v_mov_b32_e32 v92, v0
	v_mov_b32_e32 v93, v0
	v_mov_b32_e32 v94, v0
	v_mov_b32_e32 v95, v0
	v_mov_b32_e32 v100, v0
	v_mov_b32_e32 v101, v0
	v_mov_b32_e32 v102, v0
	v_mov_b32_e32 v103, v0
	v_mov_b32_e32 v108, v0
	v_mov_b32_e32 v109, v0
	v_mov_b32_e32 v110, v0
	v_mov_b32_e32 v111, v0
	v_mov_b32_e32 v116, v0
	v_mov_b32_e32 v117, v0
	v_mov_b32_e32 v118, v0
	v_mov_b32_e32 v119, v0
	v_mov_b32_e32 v72, v0
	v_mov_b32_e32 v73, v0
	v_mov_b32_e32 v74, v0
	v_mov_b32_e32 v75, v0
	v_mov_b32_e32 v80, v0
	v_mov_b32_e32 v81, v0
	v_mov_b32_e32 v82, v0
	v_mov_b32_e32 v83, v0
	v_mov_b32_e32 v88, v0
	v_mov_b32_e32 v89, v0
	v_mov_b32_e32 v90, v0
	v_mov_b32_e32 v91, v0
	v_mov_b32_e32 v96, v0
	v_mov_b32_e32 v97, v0
	v_mov_b32_e32 v98, v0
	v_mov_b32_e32 v99, v0
	v_mov_b32_e32 v104, v0
	v_mov_b32_e32 v105, v0
	v_mov_b32_e32 v106, v0
	v_mov_b32_e32 v107, v0
	v_mov_b32_e32 v112, v0
	v_mov_b32_e32 v113, v0
	v_mov_b32_e32 v114, v0
	v_mov_b32_e32 v115, v0
	v_mov_b32_e32 v120, v0
	v_mov_b32_e32 v121, v0
	v_mov_b32_e32 v122, v0
	v_mov_b32_e32 v123, v0
	v_mov_b32_e32 v124, v0
	v_mov_b32_e32 v125, v0
	v_mov_b32_e32 v126, v0
	v_mov_b32_e32 v127, v0

;     __device__ __forceinline__ const char* aptr(const Unit& u, const Gemm& g) const { return (const char*)g.A + (long)(u.pm >> 4) * g.adj; }
;     __device__ __forceinline__ const char* bptr(const Unit&, const Gemm& g) const { return (const char*)g.Bt; }
; #define PG8_STAGE(bufoff, gbase, voff) do { _Pragma("unroll") for (int _i = 0; _i < 2; ++_i) \
;         __builtin_amdgcn_global_load_lds((const unsigned*)((const char*)(gbase) + (voff)[_i]), (PG8_LAS unsigned*)(lds + (bufoff) + ldsw + _i * 8192), 16, 0, 0); } while (0)
; #define PG8_WAIT_V(n) asm volatile("s_waitcnt vmcnt(" #n ")" ::: "memory")
; #define PG8_BAR __builtin_amdgcn_s_barrier()
; template <class Epi, class Sched, bool ALIGN_EPI = false, bool SP2 = false>
; __device__ __forceinline__ void gemm_phase(PG8_LAS unsigned char* lds, const Gemm g, const Sched& S, const Epi& E) {
;     ...
;     f32x4 acc[2][2][4][2];
; #pragma unroll
;     for (int a = 0; a < 2; ++a)
; #pragma unroll
;         for (int b = 0; b < 2; ++b)
; #pragma unroll
;             for (int m = 0; m < 4; ++m)
; #pragma unroll
;                 for (int n = 0; n < 2; ++n) acc[a][b][m][n] = (f32x4){0.f, 0.f, 0.f, 0.f};
;     ...
;     const char* cA = S.aptr(cur, g) + (size_t)cur.pm * tstep; const char* cB = S.bptr(cur, g) + (size_t)cur.pn * tstep;
;     S.a_ready(cur);
;     if constexpr (SP2) {
;         PG8_STAGE(PG8_SB(0, 0), cB, voffB); PG8_STAGE(PG8_SB(0, 1), cB + hstep, voffB); PG8_STAGE(PG8_SA(0, 0), cA, voffA); PG8_STAGE(PG8_SA(0, 1), cA + hstep, voffA);
;         if (wr == 1) PG8_BAR;
;         PG8_WAIT_V(2); PG8_BAR;
;         PG8_STAGE(PG8_SB(1, 0), cB + kstep, voffB); PG8_STAGE(PG8_SA(1, 0), cA + kstep, voffA); PG8_STAGE(PG8_SB(1, 1), cB + hstep + kstep, voffB);
;         PG8_WAIT_V(6); PG8_BAR;
.LBB0_468:
	s_and_b64 s[10:11], s[24:25], exec
	s_cselect_b32 s61, 0x200, 2
	s_cselect_b32 s62, s86, 32
	s_add_u32 s43, s90, s28
	s_mul_i32 s10, s87, 0xc00
	s_addc_u32 s49, s91, s29
	s_ashr_i32 s11, s10, 31
	s_lshl_b64 s[10:11], s[10:11], 2
	s_waitcnt lgkmcnt(0)
	s_add_u32 s63, s30, s10
	s_addc_u32 s64, s31, s11
	s_add_u32 s10, s90, s26
	s_addc_u32 s11, s91, s27
	s_lshl_b32 s26, s97, 5
	s_and_b32 s26, s26, 0xe0
	s_add_i32 s26, s26, s46
	v_bfe_u32 v16, v13, 4, 2
	s_and_b64 s[24:25], s[24:25], exec
	v_and_b32_e32 v15, 15, v13
	v_lshlrev_b32_e32 v192, 4, v16
	v_lshlrev_b32_e32 v13, 2, v13
	s_cselect_b32 s30, s80, s26
	s_and_b32 s26, s48, 3
	v_lshlrev_b32_e32 v17, 3, v16
	v_lshl_or_b32 v16, v15, 6, v192
	s_lshl_b32 s24, s47, 13
	v_and_b32_e32 v13, 32, v13
	s_add_i32 m0, s55, 0x18000
	v_lshl_add_u64 v[6:7], v[6:7], 0, s[36:37]
	v_bitop3_b32 v18, v16, s24, v13 bitop3:0xde
	s_lshl_b32 s24, s26, 12
	s_waitcnt vmcnt(2)
	s_barrier
	global_load_lds_dwordx4 v[6:7], off
	v_lshl_add_u64 v[4:5], v[4:5], 0, s[36:37]
	s_add_i32 m0, s55, 0x1a000
	s_add_i32 s65, s55, 0x8000
	s_add_i32 s66, s55, 0xa000
	v_bitop3_b32 v246, v16, s24, v13 bitop3:0xde
	global_load_lds_dwordx4 v[4:5], off
	v_lshl_add_u64 v[0:1], v[0:1], 0, s[36:37]
	s_mov_b32 m0, s65
	s_add_u32 s24, s50, 0x40080
	global_load_lds_dwordx4 v[0:1], off
	v_lshl_add_u64 v[0:1], v[2:3], 0, s[36:37]
	s_mov_b32 m0, s66
	s_addc_u32 s25, s51, 0
	global_load_lds_dwordx4 v[0:1], off
	s_add_i32 m0, s55, 0x1c000
	v_lshl_add_u64 v[0:1], s[24:25], 0, v[198:199]
	global_load_lds_dwordx4 v[0:1], off
	v_lshl_add_u64 v[0:1], s[24:25], 0, v[194:195]
	s_add_i32 m0, s55, 0x1e000
	s_cmpk_lt_u32 s45, 0x100
	global_load_lds_dwordx4 v[0:1], off
	v_lshl_or_b32 v247, s26, 5, v17
	s_cselect_b64 s[24:25], -1, 0
	s_and_b32 s27, s45, 0xfffff00
	s_lshl_b32 s26, s26, 6
	s_or_b32 s26, s26, s27
	s_add_u32 s67, s41, 0xeb00000
	s_addc_u32 s68, s44, 0
	v_or3_b32 v0, s26, v192, v15
	s_add_u32 s26, s41, 0x1b700000
	s_addc_u32 s27, s44, 0
	s_add_u32 s69, s19, 0xe00000
	s_addc_u32 s70, s40, 0
	s_add_u32 s28, s19, 0x1000000
	s_addc_u32 s29, s40, 0
	v_lshlrev_b32_e32 v248, 4, v0
	s_add_u32 s71, s43, 0xd700000
	v_lshlrev_b32_e32 v0, 14, v12
	s_addc_u32 s72, s49, 0
	s_ashr_i32 s19, s30, 5
	v_and_b32_e32 v0, 0xffff8000, v0
	s_mul_hi_i32 s31, s19, 0x1c00000
	s_mul_i32 s19, s19, 0x1c00000
	v_lshl_add_u32 v0, v11, 11, v0
	v_and_b32_e32 v1, 1, v12
	s_add_u32 s19, s71, s19
	v_lshl_or_b32 v0, v1, 6, v0
	s_addc_u32 s31, s72, s31
	s_lshl_b32 s30, s30, 17
	v_lshl_add_u32 v204, v14, 1, v0
	v_lshlrev_b32_e32 v0, 14, v8
	s_and_b32 s30, s30, 0x3e0000
	v_and_b32_e32 v0, 0xffff8000, v0
	s_add_u32 s19, s19, s30
	v_lshl_add_u32 v0, v9, 11, v0
	v_and_b32_e32 v1, 1, v8
	s_waitcnt vmcnt(6)
	s_addc_u32 s31, s31, 0
	v_lshl_or_b32 v0, v1, 6, v0
	s_add_u32 s30, s19, 0x800000
	v_lshl_add_u32 v206, v10, 1, v0
	v_mov_b32_e32 v0, 0
	v_lshl_or_b32 v245, s47, 6, v15
	s_addc_u32 s31, s31, 0
	v_lshl_add_u64 v[202:203], s[10:11], 0, v[192:193]
	v_mov_b32_e32 v205, v193
	v_mov_b32_e32 v207, v193
	s_mov_b32 s43, 0
	v_add_u32_e32 v249, 0, v18
	s_mov_b32 s73, 0
	v_mov_b32_e32 v1, v0
	v_mov_b32_e32 v2, v0
	v_mov_b32_e32 v3, v0
	v_mov_b32_e32 v4, v0
	v_mov_b32_e32 v5, v0
	v_mov_b32_e32 v6, v0
	v_mov_b32_e32 v7, v0
	v_mov_b32_e32 v8, v0
	v_mov_b32_e32 v9, v0
	v_mov_b32_e32 v10, v0
	v_mov_b32_e32 v11, v0
	v_mov_b32_e32 v12, v0
	v_mov_b32_e32 v13, v0
	v_mov_b32_e32 v14, v0
	v_mov_b32_e32 v15, v0
	v_mov_b32_e32 v16, v0
	v_mov_b32_e32 v17, v0
	v_mov_b32_e32 v18, v0
	v_mov_b32_e32 v19, v0
	v_mov_b32_e32 v20, v0
	v_mov_b32_e32 v21, v0
	v_mov_b32_e32 v22, v0
	v_mov_b32_e32 v23, v0
	v_mov_b32_e32 v24, v0
	v_mov_b32_e32 v25, v0
	v_mov_b32_e32 v26, v0
	v_mov_b32_e32 v27, v0
	v_mov_b32_e32 v28, v0
	v_mov_b32_e32 v29, v0
	v_mov_b32_e32 v30, v0
	v_mov_b32_e32 v31, v0
	v_mov_b32_e32 v32, v0
	v_mov_b32_e32 v33, v0
	v_mov_b32_e32 v34, v0
	v_mov_b32_e32 v35, v0
	v_mov_b32_e32 v36, v0
	v_mov_b32_e32 v37, v0
	v_mov_b32_e32 v38, v0
	v_mov_b32_e32 v39, v0
	v_mov_b32_e32 v40, v0
	v_mov_b32_e32 v41, v0
	v_mov_b32_e32 v42, v0
	v_mov_b32_e32 v43, v0
	v_mov_b32_e32 v44, v0
	v_mov_b32_e32 v45, v0
	v_mov_b32_e32 v46, v0
	v_mov_b32_e32 v47, v0
	v_mov_b32_e32 v48, v0
	v_mov_b32_e32 v49, v0
	v_mov_b32_e32 v50, v0
	v_mov_b32_e32 v51, v0
	v_mov_b32_e32 v52, v0
	v_mov_b32_e32 v53, v0
	v_mov_b32_e32 v54, v0
	v_mov_b32_e32 v55, v0
	v_mov_b32_e32 v56, v0
	v_mov_b32_e32 v57, v0
	v_mov_b32_e32 v58, v0
	v_mov_b32_e32 v59, v0
	v_mov_b32_e32 v60, v0
	v_mov_b32_e32 v61, v0
	v_mov_b32_e32 v62, v0
	v_mov_b32_e32 v63, v0
	v_mov_b32_e32 v64, v0
	v_mov_b32_e32 v65, v0
	v_mov_b32_e32 v66, v0
	v_mov_b32_e32 v67, v0
	v_mov_b32_e32 v68, v0
	v_mov_b32_e32 v69, v0
	v_mov_b32_e32 v70, v0
	v_mov_b32_e32 v71, v0
	v_mov_b32_e32 v72, v0
	v_mov_b32_e32 v73, v0
	v_mov_b32_e32 v74, v0
	v_mov_b32_e32 v75, v0
	v_mov_b32_e32 v76, v0
	v_mov_b32_e32 v77, v0
	v_mov_b32_e32 v78, v0
	v_mov_b32_e32 v79, v0
	v_mov_b32_e32 v80, v0
	v_mov_b32_e32 v81, v0
	v_mov_b32_e32 v82, v0
	v_mov_b32_e32 v83, v0
	v_mov_b32_e32 v84, v0
	v_mov_b32_e32 v85, v0
	v_mov_b32_e32 v86, v0
	v_mov_b32_e32 v87, v0
	v_mov_b32_e32 v88, v0
	v_mov_b32_e32 v89, v0
	v_mov_b32_e32 v90, v0
	v_mov_b32_e32 v91, v0
	v_mov_b32_e32 v92, v0
	v_mov_b32_e32 v93, v0
	v_mov_b32_e32 v94, v0
	v_mov_b32_e32 v95, v0
	v_mov_b32_e32 v96, v0
	v_mov_b32_e32 v97, v0
	v_mov_b32_e32 v98, v0
	v_mov_b32_e32 v99, v0
	v_mov_b32_e32 v100, v0
	v_mov_b32_e32 v101, v0
	v_mov_b32_e32 v102, v0
	v_mov_b32_e32 v103, v0
	v_mov_b32_e32 v104, v0
	v_mov_b32_e32 v105, v0
	v_mov_b32_e32 v106, v0
	v_mov_b32_e32 v107, v0
	v_mov_b32_e32 v108, v0
	v_mov_b32_e32 v109, v0
	v_mov_b32_e32 v110, v0
	v_mov_b32_e32 v111, v0
	v_mov_b32_e32 v112, v0
	v_mov_b32_e32 v113, v0
	v_mov_b32_e32 v114, v0
	v_mov_b32_e32 v115, v0
	v_mov_b32_e32 v116, v0
	v_mov_b32_e32 v117, v0
	v_mov_b32_e32 v118, v0
	v_mov_b32_e32 v119, v0
	v_mov_b32_e32 v120, v0
	v_mov_b32_e32 v121, v0
	v_mov_b32_e32 v122, v0
	v_mov_b32_e32 v123, v0
	v_mov_b32_e32 v124, v0
	v_mov_b32_e32 v125, v0
	v_mov_b32_e32 v126, v0
	v_mov_b32_e32 v127, v0
	s_mov_b64 s[44:45], s[34:35]
	s_mov_b32 s4, 0x10000
	s_mov_b32 s5, 0x12000
	s_mov_b32 s6, 0x14000
	s_mov_b32 s7, 0x16000
	s_mov_b32 s79, 0x18000
	s_mov_b32 s85, 0x1a000
	s_mov_b32 s87, 0x1c000
	s_barrier
	s_branch .LBB0_471

;     __device__ __forceinline__ const char* aptr(const Unit& u, const Gemm& g) const { return (const char*)g.A + (long)(u.pm >> 4) * g.adj; }
;     __device__ __forceinline__ const char* bptr(const Unit&, const Gemm& g) const { return (const char*)g.Bt; }
;     __device__ __forceinline__ bool next(int i, Unit& u) const { const int r = i / 9, tile = t0 + r * ts; if (r >= nr || tile >= 512) return false; u.pm = tile >> 2; u.pn = tile & 3; u.kind = i % 9; return true; }
; template <class Epi, class Sched, bool ALIGN_EPI = false, bool SP2 = false>
; __device__ __forceinline__ void gemm_phase(PG8_LAS unsigned char* lds, const Gemm g, const Sched& S, const Epi& E) {
;     ...
;         const bool has_next = S.next(ui + 1, nxt);
;         const char* nA = has_next ? S.aptr(nxt, g) + (size_t)nxt.pm * tstep : cA; const char* nB = has_next ? S.bptr(nxt, g) + (size_t)nxt.pn * tstep : cB;
;     ...
;         if (epi_now) {
; #pragma unroll
;         for (int a = 0; a < 2; ++a)
; #pragma unroll
;             for (int b = 0; b < 2; ++b)
; #pragma unroll
;                 for (int m = 0; m < 4; ++m)
; #pragma unroll
;                     for (int n = 0; n < 2; ++n) acc[a][b][m][n] = (f32x4){0.f, 0.f, 0.f, 0.f};
;         }
;         cur = nxt; cA = nA; cB = nB; ++ui;
.LBB0_576:
	s_ashr_i32 s29, s28, 31
	s_lshl_b64 s[10:11], s[28:29], 19
	s_add_u32 s30, s3, s10
	s_addc_u32 s31, s8, s11
	s_and_b64 s[10:11], s[40:41], exec
	s_cselect_b32 s29, s31, s45
	s_cselect_b32 s43, s30, s44
	s_ashr_i32 s27, s26, 31
	s_lshl_b64 s[10:11], s[26:27], 19
	s_add_u32 s34, s14, s10
	s_addc_u32 s35, s18, s11
	s_and_b64 s[10:11], s[40:41], exec
	s_cselect_b32 s27, s35, s47
	s_cselect_b32 s60, s34, s46
	s_add_u32 s44, s44, 0x40080
	s_addc_u32 s45, s45, 0
	s_add_u32 s61, s46, 0x100
	v_mov_b32_e32 v0, 0
	s_addc_u32 s62, s47, 0
	s_mov_b32 s63, -2
	v_mov_b32_e32 v1, v0
	v_mov_b32_e32 v2, v0
	v_mov_b32_e32 v3, v0
	v_mov_b32_e32 v8, v0
	v_mov_b32_e32 v9, v0
	v_mov_b32_e32 v10, v0
	v_mov_b32_e32 v11, v0
	v_mov_b32_e32 v16, v0
	v_mov_b32_e32 v17, v0
	v_mov_b32_e32 v18, v0
	v_mov_b32_e32 v19, v0
	v_mov_b32_e32 v24, v0
	v_mov_b32_e32 v25, v0
	v_mov_b32_e32 v26, v0
	v_mov_b32_e32 v27, v0
	v_mov_b32_e32 v32, v0
	v_mov_b32_e32 v33, v0
	v_mov_b32_e32 v34, v0
	v_mov_b32_e32 v35, v0
	v_mov_b32_e32 v40, v0
	v_mov_b32_e32 v41, v0
	v_mov_b32_e32 v42, v0
	v_mov_b32_e32 v43, v0
	v_mov_b32_e32 v48, v0
	v_mov_b32_e32 v49, v0
	v_mov_b32_e32 v50, v0
	v_mov_b32_e32 v51, v0
	v_mov_b32_e32 v56, v0
	v_mov_b32_e32 v57, v0
	v_mov_b32_e32 v58, v0
	v_mov_b32_e32 v59, v0
	v_mov_b32_e32 v4, v0
	v_mov_b32_e32 v5, v0
	v_mov_b32_e32 v6, v0
	v_mov_b32_e32 v7, v0
	v_mov_b32_e32 v12, v0
	v_mov_b32_e32 v13, v0
	v_mov_b32_e32 v14, v0
	v_mov_b32_e32 v15, v0
	v_mov_b32_e32 v20, v0
	v_mov_b32_e32 v21, v0
	v_mov_b32_e32 v22, v0
	v_mov_b32_e32 v23, v0
	v_mov_b32_e32 v28, v0
	v_mov_b32_e32 v29, v0
	v_mov_b32_e32 v30, v0
	v_mov_b32_e32 v31, v0
	v_mov_b32_e32 v36, v0
	v_mov_b32_e32 v37, v0
	v_mov_b32_e32 v38, v0
	v_mov_b32_e32 v39, v0
	v_mov_b32_e32 v44, v0
	v_mov_b32_e32 v45, v0
	v_mov_b32_e32 v46, v0
	v_mov_b32_e32 v47, v0
	v_mov_b32_e32 v52, v0
	v_mov_b32_e32 v53, v0
	v_mov_b32_e32 v54, v0
	v_mov_b32_e32 v55, v0
	v_mov_b32_e32 v60, v0
	v_mov_b32_e32 v61, v0
	v_mov_b32_e32 v62, v0
	v_mov_b32_e32 v63, v0
	v_mov_b32_e32 v64, v0
	v_mov_b32_e32 v65, v0
	v_mov_b32_e32 v66, v0
	v_mov_b32_e32 v67, v0
	v_mov_b32_e32 v72, v0
	v_mov_b32_e32 v73, v0
	v_mov_b32_e32 v74, v0
	v_mov_b32_e32 v75, v0
	v_mov_b32_e32 v80, v0
	v_mov_b32_e32 v81, v0
	v_mov_b32_e32 v82, v0
	v_mov_b32_e32 v83, v0
	v_mov_b32_e32 v88, v0
	v_mov_b32_e32 v89, v0
	v_mov_b32_e32 v90, v0
	v_mov_b32_e32 v91, v0
	v_mov_b32_e32 v96, v0
	v_mov_b32_e32 v97, v0
	v_mov_b32_e32 v98, v0
	v_mov_b32_e32 v99, v0
	v_mov_b32_e32 v104, v0
	v_mov_b32_e32 v105, v0
	v_mov_b32_e32 v106, v0
	v_mov_b32_e32 v107, v0
	v_mov_b32_e32 v112, v0
	v_mov_b32_e32 v113, v0
	v_mov_b32_e32 v114, v0
	v_mov_b32_e32 v115, v0
	v_mov_b32_e32 v120, v0
	v_mov_b32_e32 v121, v0
	v_mov_b32_e32 v122, v0
	v_mov_b32_e32 v123, v0
	v_mov_b32_e32 v68, v0
	v_mov_b32_e32 v69, v0
	v_mov_b32_e32 v70, v0
	v_mov_b32_e32 v71, v0
	v_mov_b32_e32 v76, v0
	v_mov_b32_e32 v77, v0
	v_mov_b32_e32 v78, v0
	v_mov_b32_e32 v79, v0
	v_mov_b32_e32 v84, v0
	v_mov_b32_e32 v85, v0
	v_mov_b32_e32 v86, v0
	v_mov_b32_e32 v87, v0
	v_mov_b32_e32 v92, v0
	v_mov_b32_e32 v93, v0
	v_mov_b32_e32 v94, v0
	v_mov_b32_e32 v95, v0
	v_mov_b32_e32 v100, v0
	v_mov_b32_e32 v101, v0
	v_mov_b32_e32 v102, v0
	v_mov_b32_e32 v103, v0
	v_mov_b32_e32 v108, v0
	v_mov_b32_e32 v109, v0
	v_mov_b32_e32 v110, v0
	v_mov_b32_e32 v111, v0
	v_mov_b32_e32 v116, v0
	v_mov_b32_e32 v117, v0
	v_mov_b32_e32 v118, v0
	v_mov_b32_e32 v119, v0
	v_mov_b32_e32 v124, v0
	v_mov_b32_e32 v125, v0
	v_mov_b32_e32 v126, v0
	v_mov_b32_e32 v127, v0
